# v45: v39 + RG-LRU pass 1: the four A-fragment LDS reads of each 16-token tile issued up front into separate registers behind counted lgkmcnt waits (was read / wait 0 / MFMA per k-slice)
# speedup vs baseline: 1.0065x; 1.0065x over previous
.LBB0_401:
	v_mad_u32_u24 v81, v80, s3, v115
	ds_read_b128 v[76:79], v81
	ds_read_b128 v[146:149], v81 offset:64
	ds_read_b128 v[228:231], v81 offset:128
	ds_read_b128 v[232:235], v81 offset:192
	v_add_u32_e32 v80, -16, v80
	s_waitcnt lgkmcnt(3)
	v_mfma_f32_16x16x32_bf16 v[134:137], v[76:79], v[0:3], 0
	v_mfma_f32_16x16x32_bf16 v[138:141], v[76:79], v[16:19], 0
	v_mfma_f32_16x16x32_bf16 v[142:145], v[76:79], v[32:35], 0
	v_mfma_f32_16x16x32_bf16 v[76:79], v[76:79], v[48:51], 0
	s_waitcnt lgkmcnt(2)
	v_mfma_f32_16x16x32_bf16 v[134:137], v[146:149], v[4:7], v[134:137]
	v_mfma_f32_16x16x32_bf16 v[138:141], v[146:149], v[20:23], v[138:141]
	v_mfma_f32_16x16x32_bf16 v[142:145], v[146:149], v[36:39], v[142:145]
	v_mfma_f32_16x16x32_bf16 v[76:79], v[146:149], v[52:55], v[76:79]
	s_waitcnt lgkmcnt(1)
	v_mfma_f32_16x16x32_bf16 v[134:137], v[228:231], v[8:11], v[134:137]
	v_mfma_f32_16x16x32_bf16 v[138:141], v[228:231], v[24:27], v[138:141]
	v_mfma_f32_16x16x32_bf16 v[142:145], v[228:231], v[40:43], v[142:145]
	v_mfma_f32_16x16x32_bf16 v[76:79], v[228:231], v[56:59], v[76:79]
	s_waitcnt lgkmcnt(0)
	v_mfma_f32_16x16x32_bf16 v[134:137], v[232:235], v[12:15], v[134:137]
	s_nop 7
	v_fmamk_f32 v81, v134, 0xbfb8aa3b, v125
	s_nop 0
	v_exp_f32_e32 v81, v81
	v_mfma_f32_16x16x32_bf16 v[142:145], v[232:235], v[44:47], v[142:145]
	v_add_f32_e32 v81, 1.0, v81
	v_rcp_f32_e32 v81, v81
	v_mfma_f32_16x16x32_bf16 v[138:141], v[232:235], v[28:31], v[138:141]
	s_nop 4
	v_fmamk_f32 v82, v142, 0xbfb8aa3b, v126
	s_nop 0
	v_mul_f32_e32 v81, v81, v127
	s_nop 0
	v_exp_f32_e32 v83, v81
	v_exp_f32_e32 v82, v82
	v_fmamk_f32 v97, v143, 0xbfb8aa3b, v126
	v_fma_f32 v81, -v83, v83, 1.0
	v_add_f32_e32 v82, 1.0, v82
	v_max_f32_e32 v81, 0, v81
	v_rcp_f32_e32 v82, v82
	v_sqrt_f32_e32 v81, v81
	v_exp_f32_e32 v97, v97
	v_mfma_f32_16x16x32_bf16 v[76:79], v[232:235], v[60:63], v[76:79]
	v_mul_f32_e32 v134, v82, v81
	v_fmamk_f32 v82, v135, 0xbfb8aa3b, v125
	s_nop 0
	v_exp_f32_e32 v82, v82
	v_add_f32_e32 v97, 1.0, v97
	v_rcp_f32_e32 v97, v97
	v_add_u32_e32 v81, s4, v122
	v_add_f32_e32 v82, 1.0, v82
	v_rcp_f32_e32 v82, v82
	ds_read2_b32 v[146:147], v81 offset1:16
	ds_read2_b32 v[150:151], v81 offset0:132 offset1:148
	v_add_u32_e32 v81, 0x400, v81
	v_mul_f32_e32 v82, v82, v127
	v_exp_f32_e32 v143, v82
	ds_read2_b32 v[156:157], v81 offset0:140 offset1:156
	ds_read2_b32 v[154:155], v81 offset0:8 offset1:24
	s_waitcnt lgkmcnt(2)
	v_mov_b32_e32 v142, v150
	v_fma_f32 v82, -v143, v143, 1.0
	v_max_f32_e32 v82, 0, v82
	v_sqrt_f32_e32 v82, v82
	s_waitcnt lgkmcnt(0)
	v_mov_b32_e32 v152, v154
	v_fmamk_f32 v76, v76, 0xbfb8aa3b, v129
	s_nop 0
	v_mul_f32_e32 v148, v97, v82
	v_fmamk_f32 v82, v136, 0xbfb8aa3b, v125
	s_nop 0
	v_exp_f32_e32 v82, v82
	v_fmamk_f32 v97, v144, 0xbfb8aa3b, v126
	s_nop 0
	v_exp_f32_e32 v97, v97
	v_add_f32_e32 v82, 1.0, v82
	v_rcp_f32_e32 v82, v82
	v_exp_f32_e32 v76, v76
	v_add_f32_e32 v97, 1.0, v97
	v_rcp_f32_e32 v97, v97
	v_mul_f32_e32 v82, v82, v127
	v_exp_f32_e32 v153, v82
	v_add_f32_e32 v76, 1.0, v76
	v_rcp_f32_e32 v76, v76
	v_fmamk_f32 v77, v77, 0xbfb8aa3b, v129
	v_fma_f32 v82, -v153, v153, 1.0
	v_max_f32_e32 v82, 0, v82
	v_sqrt_f32_e32 v82, v82
	v_exp_f32_e32 v77, v77
	v_fmamk_f32 v78, v78, 0xbfb8aa3b, v129
	v_mul_f32_e32 v136, v97, v82
	v_fmamk_f32 v82, v137, 0xbfb8aa3b, v125
	v_exp_f32_e32 v82, v82
	v_fmamk_f32 v97, v145, 0xbfb8aa3b, v126
	v_exp_f32_e32 v97, v97
	v_add_f32_e32 v82, 1.0, v82
	v_rcp_f32_e32 v82, v82
	v_mov_b32_e32 v145, v156
	v_add_f32_e32 v97, 1.0, v97
	v_rcp_f32_e32 v97, v97
	v_mul_f32_e32 v82, v82, v127
	v_exp_f32_e32 v144, v82
	v_add_f32_e32 v77, 1.0, v77
	v_rcp_f32_e32 v77, v77
	v_fma_f32 v82, -v144, v144, 1.0
	v_max_f32_e32 v82, 0, v82
	v_sqrt_f32_e32 v82, v82
	v_mul_f32_e32 v81, v144, v153
	v_mul_f32_e32 v81, v143, v81
	v_mul_f32_e32 v81, v83, v81
	v_mul_f32_e32 v97, v97, v82
	v_mul_f32_e32 v82, 0, v144
	v_pk_fma_f32 v[158:159], v[144:145], v[96:97], v[82:83] op_sel_hi:[1,1,0]
	v_mul_f32_e32 v82, v154, v136
	v_mov_b32_e32 v137, v159
	v_pk_fma_f32 v[136:137], v[152:153], v[136:137], v[82:83] op_sel_hi:[1,1,0]
	v_mul_f32_e32 v82, v150, v148
	v_mov_b32_e32 v149, v137
	v_pk_fma_f32 v[136:137], v[142:143], v[148:149], v[82:83] op_sel_hi:[1,1,0]
	v_mov_b32_e32 v82, v146
	v_mov_b32_e32 v135, v137
	v_mul_f32_e32 v136, v83, v137
	v_pk_fma_f32 v[134:135], v[82:83], v[134:135], v[136:137] op_sel_hi:[1,1,0]
	ds_bpermute_b32 v82, v132, v81
	ds_bpermute_b32 v142, v131, v81
	ds_bpermute_b32 v146, v133, v81
	ds_bpermute_b32 v150, v93, v81
	v_fmamk_f32 v81, v138, 0xbfb8aa3b, v130
	v_exp_f32_e32 v81, v81
	v_exp_f32_e32 v78, v78
	v_fmamk_f32 v79, v79, 0xbfb8aa3b, v129
	v_add_f32_e32 v81, 1.0, v81
	v_rcp_f32_e32 v81, v81
	v_add_f32_e32 v78, 1.0, v78
	v_rcp_f32_e32 v78, v78
	v_exp_f32_e32 v79, v79
	v_mul_f32_e32 v81, v81, v128
	v_exp_f32_e32 v153, v81
	v_add_f32_e32 v79, 1.0, v79
	v_rcp_f32_e32 v79, v79
	v_mov_b32_e32 v97, v157
	v_fma_f32 v81, -v153, v153, 1.0
	v_max_f32_e32 v81, 0, v81
	v_sqrt_f32_e32 v81, v81
	v_mov_b32_e32 v158, v155
	v_mov_b32_e32 v152, v147
	ds_bpermute_b32 v136, v132, v134
	v_mul_f32_e32 v76, v76, v81
	v_fmamk_f32 v81, v139, 0xbfb8aa3b, v130
	v_exp_f32_e32 v81, v81
	ds_bpermute_b32 v144, v131, v134
	ds_bpermute_b32 v148, v133, v134
	ds_bpermute_b32 v134, v93, v134
	v_add_f32_e32 v81, 1.0, v81
	v_rcp_f32_e32 v81, v81
	s_addk_i32 s4, 0xdf00
	s_cmpk_lg_i32 s4, 0x6700
	v_mul_f32_e32 v81, v81, v128
	s_nop 0
	v_exp_f32_e32 v139, v81
	s_nop 0
	v_fma_f32 v81, -v139, v139, 1.0
	v_max_f32_e32 v81, 0, v81
	v_sqrt_f32_e32 v81, v81
	s_nop 0
	v_mul_f32_e32 v154, v77, v81
	v_fmamk_f32 v77, v140, 0xbfb8aa3b, v130
	s_nop 0
	v_exp_f32_e32 v77, v77
	s_nop 0
	v_add_f32_e32 v77, 1.0, v77
	v_rcp_f32_e32 v77, v77
	s_nop 0
	v_mul_f32_e32 v77, v77, v128
	s_nop 0
	v_exp_f32_e32 v159, v77
	s_nop 0
	v_fma_f32 v77, -v159, v159, 1.0
	v_max_f32_e32 v77, 0, v77
	v_sqrt_f32_e32 v77, v77
	s_nop 0
	v_mul_f32_e32 v78, v78, v77
	v_fmamk_f32 v77, v141, 0xbfb8aa3b, v130
	s_nop 0
	v_exp_f32_e32 v77, v77
	s_nop 0
	v_add_f32_e32 v77, 1.0, v77
	v_rcp_f32_e32 v77, v77
	s_nop 0
	v_mul_f32_e32 v77, v77, v128
	s_nop 0
	v_exp_f32_e32 v140, v77
	s_nop 0
	v_fma_f32 v77, -v140, v140, 1.0
	v_max_f32_e32 v77, 0, v77
	v_sqrt_f32_e32 v77, v77
	v_mul_f32_e32 v138, 0, v140
	v_mul_f32_e32 v141, v79, v77
	v_pk_fma_f32 v[156:157], v[140:141], v[96:97], v[138:139] op_sel_hi:[1,1,0]
	v_mul_f32_e32 v138, v78, v155
	v_mov_b32_e32 v79, v157
	v_pk_fma_f32 v[78:79], v[78:79], v[158:159], v[138:139] op_sel_hi:[1,1,0]
	v_mov_b32_e32 v138, v151
	v_mov_b32_e32 v155, v79
	v_mul_f32_e32 v78, v154, v151
	v_mul_f32_e32 v77, v140, v159
	v_pk_fma_f32 v[78:79], v[154:155], v[138:139], v[78:79] op_sel_hi:[1,1,0]
	v_mul_f32_e32 v81, v139, v77
	v_mov_b32_e32 v77, v79
	v_mul_f32_e32 v78, v79, v153
	v_pk_fma_f32 v[76:77], v[76:77], v[152:153], v[78:79] op_sel_hi:[1,1,0]
	ds_bpermute_b32 v137, v132, v76
	v_mul_f32_e32 v77, v153, v81
	ds_bpermute_b32 v83, v132, v77
	ds_bpermute_b32 v143, v131, v77
	ds_bpermute_b32 v145, v131, v76
	ds_bpermute_b32 v147, v133, v77
	ds_bpermute_b32 v149, v133, v76
	ds_bpermute_b32 v151, v93, v77
	ds_bpermute_b32 v135, v93, v76
	s_waitcnt lgkmcnt(6)
	v_pk_fma_f32 v[76:77], v[110:111], v[82:83], v[136:137]
	s_waitcnt lgkmcnt(4)
	v_pk_fma_f32 v[76:77], v[76:77], v[142:143], v[144:145]
	s_waitcnt lgkmcnt(2)
	v_pk_fma_f32 v[76:77], v[76:77], v[146:147], v[148:149]
	s_waitcnt lgkmcnt(0)
	v_pk_fma_f32 v[110:111], v[76:77], v[150:151], v[134:135]
	v_pk_mul_f32 v[76:77], v[82:83], v[142:143]
	s_nop 0
	v_pk_mul_f32 v[76:77], v[76:77], v[146:147]
	s_nop 0
	v_pk_mul_f32 v[76:77], v[76:77], v[150:151]
	s_nop 0
	v_pk_mul_f32 v[108:109], v[108:109], v[76:77]
	s_cbranch_scc1 .LBB0_401
	s_mov_b64 s[18:19], 0

.LBB0_405:
	v_add_u32_e32 v97, 0, v135
	v_add_u32_e32 v76, 0x10c00, v97
	ds_read_b128 v[76:79], v76
	v_add_u32_e32 v144, 0x10c40, v97
	ds_read_b128 v[144:147], v144
	v_add_u32_e32 v228, 0x10c80, v97
	ds_read_b128 v[228:231], v228
	v_add_u32_e32 v232, 0x10cc0, v97
	ds_read_b128 v[232:235], v232
	s_add_i32 s4, s4, -1
	v_add_u32_e32 v135, 0x1100, v135
	s_cmp_eq_u32 s4, 0
	s_waitcnt lgkmcnt(3)
	v_mfma_f32_16x16x32_bf16 v[80:83], v[76:79], v[0:3], 0
	v_mfma_f32_16x16x32_bf16 v[136:139], v[76:79], v[16:19], 0
	v_mfma_f32_16x16x32_bf16 v[140:143], v[76:79], v[32:35], 0
	v_mfma_f32_16x16x32_bf16 v[76:79], v[76:79], v[48:51], 0
	s_waitcnt lgkmcnt(2)
	v_mfma_f32_16x16x32_bf16 v[80:83], v[144:147], v[4:7], v[80:83]
	v_mfma_f32_16x16x32_bf16 v[136:139], v[144:147], v[20:23], v[136:139]
	v_mfma_f32_16x16x32_bf16 v[140:143], v[144:147], v[36:39], v[140:143]
	v_mfma_f32_16x16x32_bf16 v[76:79], v[144:147], v[52:55], v[76:79]
	s_waitcnt lgkmcnt(1)
	v_mfma_f32_16x16x32_bf16 v[80:83], v[228:231], v[8:11], v[80:83]
	v_mfma_f32_16x16x32_bf16 v[136:139], v[228:231], v[24:27], v[136:139]
	v_mfma_f32_16x16x32_bf16 v[140:143], v[228:231], v[40:43], v[140:143]
	v_mfma_f32_16x16x32_bf16 v[76:79], v[228:231], v[56:59], v[76:79]
	s_waitcnt lgkmcnt(0)
	v_mfma_f32_16x16x32_bf16 v[148:151], v[232:235], v[12:15], v[80:83]
	s_nop 7
	v_fmamk_f32 v97, v148, 0xbfb8aa3b, v125
	v_mfma_f32_16x16x32_bf16 v[80:83], v[232:235], v[28:31], v[136:139]
	s_nop 0
	v_exp_f32_e32 v97, v97
	v_mfma_f32_16x16x32_bf16 v[136:139], v[232:235], v[44:47], v[140:143]
	v_add_f32_e32 v97, 1.0, v97
	v_rcp_f32_e32 v97, v97
	s_nop 0
	v_fmamk_f32 v143, v149, 0xbfb8aa3b, v125
	s_nop 0
	v_exp_f32_e32 v143, v143
	s_nop 1
	v_fmamk_f32 v137, v137, 0xbfb8aa3b, v126
	s_nop 0
	v_exp_f32_e32 v137, v137
	v_add_f32_e32 v143, 1.0, v143
	v_rcp_f32_e32 v143, v143
	v_mfma_f32_16x16x32_bf16 v[76:79], v[232:235], v[60:63], v[76:79]
	v_add_f32_e32 v137, 1.0, v137
	v_rcp_f32_e32 v137, v137
	v_mul_f32_e32 v143, v143, v127
	v_exp_f32_e32 v143, v143
	v_fmamk_f32 v136, v136, 0xbfb8aa3b, v126
	v_exp_f32_e32 v136, v136
	v_fma_f32 v144, -v143, v143, 1.0
	v_max_f32_e32 v144, 0, v144
	v_sqrt_f32_e32 v144, v144
	v_mul_f32_e32 v97, v97, v127
	v_add_f32_e32 v136, 1.0, v136
	v_mul_f32_e32 v144, v137, v144
	v_fmamk_f32 v137, v150, 0xbfb8aa3b, v125
	v_exp_f32_e32 v137, v137
	v_fmamk_f32 v138, v138, 0xbfb8aa3b, v126
	v_rcp_f32_e32 v140, v136
	v_exp_f32_e32 v136, v97
	v_add_f32_e32 v137, 1.0, v137
	v_rcp_f32_e32 v137, v137
	v_exp_f32_e32 v138, v138
	v_fma_f32 v97, -v136, v136, 1.0
	v_mul_f32_e32 v137, v137, v127
	v_exp_f32_e32 v149, v137
	v_max_f32_e32 v97, 0, v97
	v_add_f32_e32 v138, 1.0, v138
	v_sqrt_f32_e32 v97, v97
	v_fma_f32 v137, -v149, v149, 1.0
	v_max_f32_e32 v137, 0, v137
	v_rcp_f32_e32 v138, v138
	v_sqrt_f32_e32 v137, v137
	v_add_u32_e32 v142, 0, v134
	v_mul_f32_e32 v97, v140, v97
	ds_read2_b32 v[140:141], v142 offset1:16
	ds_read2_b32 v[146:147], v142 offset0:132 offset1:148
	v_mul_f32_e32 v138, v138, v137
	v_add_u32_e32 v137, 0x400, v142
	v_fmamk_f32 v142, v151, 0xbfb8aa3b, v125
	v_exp_f32_e32 v142, v142
	v_fmamk_f32 v139, v139, 0xbfb8aa3b, v126
	v_exp_f32_e32 v139, v139
	v_add_f32_e32 v142, 1.0, v142
	v_rcp_f32_e32 v142, v142
	v_fmamk_f32 v80, v80, 0xbfb8aa3b, v130
	v_exp_f32_e32 v80, v80
	v_mul_f32_e32 v142, v142, v127
	v_exp_f32_e32 v151, v142
	v_add_f32_e32 v139, 1.0, v139
	v_rcp_f32_e32 v139, v139
	ds_read2_b32 v[152:153], v137 offset0:8 offset1:24
	v_fma_f32 v142, -v151, v151, 1.0
	v_max_f32_e32 v142, 0, v142
	v_sqrt_f32_e32 v142, v142
	ds_read2_b32 v[156:157], v137 offset0:140 offset1:156
	s_waitcnt lgkmcnt(3)
	v_mov_b32_e32 v137, v140
	v_mul_f32_e32 v140, 0, v136
	v_add_f32_e32 v80, 1.0, v80
	v_pk_fma_f32 v[158:159], v[136:137], v[96:97], v[140:141] op_sel_hi:[1,1,0]
	v_rcp_f32_e32 v80, v80
	v_mul_f32_e32 v154, v139, v142
	s_waitcnt lgkmcnt(2)
	v_mov_b32_e32 v142, v146
	v_mov_b32_e32 v145, v159
	v_mul_f32_e32 v140, v146, v144
	v_pk_fma_f32 v[144:145], v[142:143], v[144:145], v[140:141] op_sel_hi:[1,1,0]
	v_mul_f32_e32 v97, v136, v143
	s_waitcnt lgkmcnt(1)
	v_mov_b32_e32 v148, v152
	v_mov_b32_e32 v139, v145
	v_mul_f32_e32 v136, v152, v138
	v_pk_fma_f32 v[136:137], v[148:149], v[138:139], v[136:137] op_sel_hi:[1,1,0]
	v_mul_f32_e32 v80, v80, v128
	s_waitcnt lgkmcnt(0)
	v_mov_b32_e32 v150, v156
	v_mov_b32_e32 v155, v137
	v_mul_f32_e32 v136, v151, v137
	v_fmamk_f32 v76, v76, 0xbfb8aa3b, v129
	v_pk_fma_f32 v[136:137], v[150:151], v[154:155], v[136:137] op_sel_hi:[1,1,0]
	v_exp_f32_e32 v154, v80
	v_exp_f32_e32 v76, v76
	v_fmamk_f32 v77, v77, 0xbfb8aa3b, v129
	v_fma_f32 v80, -v154, v154, 1.0
	v_add_f32_e32 v76, 1.0, v76
	v_max_f32_e32 v80, 0, v80
	v_rcp_f32_e32 v76, v76
	v_sqrt_f32_e32 v80, v80
	v_exp_f32_e32 v77, v77
	v_fmamk_f32 v78, v78, 0xbfb8aa3b, v129
	v_mul_f32_e32 v155, v76, v80
	v_fmamk_f32 v76, v81, 0xbfb8aa3b, v130
	v_exp_f32_e32 v76, v76
	v_add_f32_e32 v77, 1.0, v77
	v_rcp_f32_e32 v80, v77
	v_exp_f32_e32 v78, v78
	v_add_f32_e32 v76, 1.0, v76
	v_rcp_f32_e32 v76, v76
	v_fmamk_f32 v79, v79, 0xbfb8aa3b, v129
	v_add_f32_e32 v78, 1.0, v78
	v_rcp_f32_e32 v78, v78
	v_mul_f32_e32 v76, v76, v128
	v_exp_f32_e32 v77, v76
	v_exp_f32_e32 v79, v79
	v_mul_f32_e32 v97, v149, v97
	v_fma_f32 v76, -v77, v77, 1.0
	v_max_f32_e32 v76, 0, v76
	v_sqrt_f32_e32 v76, v76
	v_add_f32_e32 v79, 1.0, v79
	v_rcp_f32_e32 v79, v79
	v_mul_f32_e32 v97, v151, v97
	v_mul_f32_e32 v80, v80, v76
	v_fmamk_f32 v76, v82, 0xbfb8aa3b, v130
	v_exp_f32_e32 v76, v76
	ds_bpermute_b32 v138, v93, v97
	ds_bpermute_b32 v142, v133, v97
	ds_bpermute_b32 v146, v131, v97
	v_add_f32_e32 v76, 1.0, v76
	v_rcp_f32_e32 v76, v76
	ds_bpermute_b32 v150, v132, v97
	v_mov_b32_e32 v97, v141
	v_mul_f32_e32 v82, v80, v147
	v_mul_f32_e32 v76, v76, v128
	v_exp_f32_e32 v159, v76
	v_mov_b32_e32 v158, v153
	ds_bpermute_b32 v140, v93, v136
	ds_bpermute_b32 v144, v133, v136
	v_fma_f32 v76, -v159, v159, 1.0
	v_max_f32_e32 v76, 0, v76
	v_sqrt_f32_e32 v76, v76
	ds_bpermute_b32 v148, v131, v136
	ds_bpermute_b32 v136, v132, v136
	v_add_u32_e32 v134, 0x2100, v134
	v_mul_f32_e32 v78, v78, v76
	v_fmamk_f32 v76, v83, 0xbfb8aa3b, v130
	s_nop 0
	v_exp_f32_e32 v76, v76
	s_nop 0
	v_add_f32_e32 v76, 1.0, v76
	v_rcp_f32_e32 v76, v76
	s_nop 0
	v_mul_f32_e32 v76, v76, v128
	s_nop 0
	v_exp_f32_e32 v83, v76
	s_nop 0
	v_fma_f32 v76, -v83, v83, 1.0
	v_max_f32_e32 v76, 0, v76
	v_sqrt_f32_e32 v76, v76
	s_nop 0
	v_mul_f32_e32 v152, v79, v76
	v_mul_f32_e32 v76, 0, v154
	v_pk_fma_f32 v[160:161], v[154:155], v[96:97], v[76:77] op_sel_hi:[1,1,0]
	v_mov_b32_e32 v76, v147
	v_mov_b32_e32 v81, v161
	v_pk_fma_f32 v[80:81], v[80:81], v[76:77], v[82:83] op_sel_hi:[1,1,0]
	v_mul_f32_e32 v76, v78, v153
	v_mov_b32_e32 v79, v81
	v_mul_f32_e32 v80, v154, v77
	v_pk_fma_f32 v[76:77], v[78:79], v[158:159], v[76:77] op_sel_hi:[1,1,0]
	v_mov_b32_e32 v82, v157
	v_mov_b32_e32 v153, v77
	v_mul_f32_e32 v76, v77, v83
	v_mul_f32_e32 v78, v159, v80
	v_pk_fma_f32 v[76:77], v[152:153], v[82:83], v[76:77] op_sel_hi:[1,1,0]
	ds_bpermute_b32 v141, v93, v76
	v_mul_f32_e32 v77, v83, v78
	ds_bpermute_b32 v139, v93, v77
	ds_bpermute_b32 v143, v133, v77
	ds_bpermute_b32 v145, v133, v76
	ds_bpermute_b32 v147, v131, v77
	ds_bpermute_b32 v149, v131, v76
	ds_bpermute_b32 v151, v132, v77
	ds_bpermute_b32 v137, v132, v76
	s_waitcnt lgkmcnt(6)
	v_pk_fma_f32 v[76:77], v[110:111], v[138:139], v[140:141]
	s_waitcnt lgkmcnt(4)
	v_pk_fma_f32 v[76:77], v[76:77], v[142:143], v[144:145]
	s_waitcnt lgkmcnt(2)
	v_pk_fma_f32 v[76:77], v[76:77], v[146:147], v[148:149]
	s_waitcnt lgkmcnt(0)
	v_pk_fma_f32 v[110:111], v[76:77], v[150:151], v[136:137]
	v_pk_mul_f32 v[76:77], v[138:139], v[142:143]
	s_nop 0
	v_pk_mul_f32 v[76:77], v[76:77], v[146:147]
	s_nop 0
	v_pk_mul_f32 v[76:77], v[76:77], v[150:151]
	s_nop 0
	v_pk_mul_f32 v[108:109], v[108:109], v[76:77]
	s_cbranch_scc0 .LBB0_405
